# v5_all_il
# speedup vs baseline: 1.2653x; 1.0179x over previous
.LBB0_73:
	s_cmp_eq_u32 s15, 0x30400
	s_mov_b32 s2, 0x10000
	s_cbranch_scc1 .LBB0_72
	s_and_b32 s2, s13, 0x10000
	s_xor_b32 s10, s2, 0x10000
	s_add_i32 s16, s21, s10
	s_add_i32 s17, s15, 0xfffd0000
	s_add_i32 s30, s16, 0x8000
	s_mov_b32 s10, s66
	s_mov_b32 s11, s67
	s_waitcnt lgkmcnt(0)
	v_add_u32_e32 v0, s2, v138
	v_add_u32_e32 v139, s2, v136
	v_xor_b32_e32 v176, 64, v0
	ds_read_b128 v[132:135], v139 offset:0
	ds_read_b128 v[140:143], v139 offset:0x800
	ds_read_b128 v[144:147], v139 offset:0x1000
	ds_read_b128 v[148:151], v139 offset:0x1800
	ds_read_b128 v[152:155], v0 offset:0
	ds_read_b128 v[156:159], v0 offset:0x800
	s_setprio 1
	ds_read_b128 v[160:163], v0 offset:0x1000
	s_mov_b32 m0, s16
	s_nop 0
	buffer_load_dwordx4 v131, s[64:67], s17 offen lds
	s_mov_b32 m0, s30
	s_nop 0
	buffer_load_dwordx4 v131, s[8:11], s17 offen lds
	s_waitcnt lgkmcnt(2)
	s_nop 0
	v_mfma_f32_16x16x32_bf16 v[126:129], v[152:155], v[132:135], v[126:129]
	v_mfma_f32_16x16x32_bf16 v[122:125], v[152:155], v[140:143], v[122:125]
	v_mfma_f32_16x16x32_bf16 v[118:121], v[152:155], v[144:147], v[118:121]
	v_mfma_f32_16x16x32_bf16 v[114:117], v[152:155], v[148:151], v[114:117]
	s_add_i32 m0, s16, 0x2000
	s_add_i32 s17, s15, 0xfffe0000
	buffer_load_dwordx4 v131, s[64:67], s17 offen lds
	ds_read_b128 v[152:155], v0 offset:0x1800
	s_waitcnt lgkmcnt(2)
	s_nop 0
	v_mfma_f32_16x16x32_bf16 v[110:113], v[156:159], v[132:135], v[110:113]
	v_mfma_f32_16x16x32_bf16 v[106:109], v[156:159], v[140:143], v[106:109]
	v_mfma_f32_16x16x32_bf16 v[102:105], v[156:159], v[144:147], v[102:105]
	v_mfma_f32_16x16x32_bf16 v[98:101], v[156:159], v[148:151], v[98:101]
	s_add_i32 m0, s16, 0xa000
	s_nop 0
	buffer_load_dwordx4 v131, s[8:11], s17 offen lds
	ds_read_b128 v[156:159], v0 offset:0x2000
	s_waitcnt lgkmcnt(2)
	s_nop 0
	v_mfma_f32_16x16x32_bf16 v[94:97], v[160:163], v[132:135], v[94:97]
	v_mfma_f32_16x16x32_bf16 v[90:93], v[160:163], v[140:143], v[90:93]
	v_mfma_f32_16x16x32_bf16 v[86:89], v[160:163], v[144:147], v[86:89]
	v_mfma_f32_16x16x32_bf16 v[82:85], v[160:163], v[148:151], v[82:85]
	s_add_i32 m0, s16, 0x4000
	s_add_i32 s17, s15, 0xffff0000
	buffer_load_dwordx4 v131, s[64:67], s17 offen lds
	ds_read_b128 v[160:163], v0 offset:0x2800
	s_waitcnt lgkmcnt(2)
	s_nop 0
	v_mfma_f32_16x16x32_bf16 v[78:81], v[152:155], v[132:135], v[78:81]
	v_mfma_f32_16x16x32_bf16 v[74:77], v[152:155], v[140:143], v[74:77]
	v_mfma_f32_16x16x32_bf16 v[70:73], v[152:155], v[144:147], v[70:73]
	v_mfma_f32_16x16x32_bf16 v[66:69], v[152:155], v[148:151], v[66:69]
	s_add_i32 m0, s16, 0xc000
	s_nop 0
	buffer_load_dwordx4 v131, s[8:11], s17 offen lds
	ds_read_b128 v[152:155], v0 offset:0x3000
	s_waitcnt lgkmcnt(2)
	s_nop 0
	v_mfma_f32_16x16x32_bf16 v[62:65], v[156:159], v[132:135], v[62:65]
	v_mfma_f32_16x16x32_bf16 v[58:61], v[156:159], v[140:143], v[58:61]
	v_mfma_f32_16x16x32_bf16 v[54:57], v[156:159], v[144:147], v[54:57]
	v_mfma_f32_16x16x32_bf16 v[50:53], v[156:159], v[148:151], v[50:53]
	s_add_i32 m0, s16, 0x6000
	s_nop 0
	buffer_load_dwordx4 v131, s[64:67], s15 offen lds
	ds_read_b128 v[156:159], v0 offset:0x3800
	s_waitcnt lgkmcnt(2)
	v_xor_b32_e32 v0, 64, v139
	v_mfma_f32_16x16x32_bf16 v[46:49], v[160:163], v[132:135], v[46:49]
	v_mfma_f32_16x16x32_bf16 v[42:45], v[160:163], v[140:143], v[42:45]
	v_mfma_f32_16x16x32_bf16 v[38:41], v[160:163], v[144:147], v[38:41]
	v_mfma_f32_16x16x32_bf16 v[34:37], v[160:163], v[148:151], v[34:37]
	s_add_i32 m0, s16, 0xe000
	s_nop 0
	buffer_load_dwordx4 v131, s[8:11], s15 offen lds
	ds_read_b128 v[160:163], v0 offset:0
	ds_read_b128 v[164:167], v0 offset:0x800
	ds_read_b128 v[168:171], v0 offset:0x1000
	s_waitcnt lgkmcnt(4)
	s_nop 0
	v_mfma_f32_16x16x32_bf16 v[30:33], v[152:155], v[132:135], v[30:33]
	v_mfma_f32_16x16x32_bf16 v[26:29], v[152:155], v[140:143], v[26:29]
	v_mfma_f32_16x16x32_bf16 v[22:25], v[152:155], v[144:147], v[22:25]
	v_mfma_f32_16x16x32_bf16 v[18:21], v[152:155], v[148:151], v[18:21]
	ds_read_b128 v[152:155], v0 offset:0x1800
	ds_read_b128 v[172:175], v176 offset:0
	ds_read_b128 v[202:205], v176 offset:0x800
	s_waitcnt lgkmcnt(6)
	s_nop 0
	v_mfma_f32_16x16x32_bf16 v[14:17], v[156:159], v[132:135], v[14:17]
	v_mfma_f32_16x16x32_bf16 v[10:13], v[156:159], v[140:143], v[10:13]
	v_mfma_f32_16x16x32_bf16 v[6:9], v[156:159], v[144:147], v[6:9]
	v_mfma_f32_16x16x32_bf16 v[2:5], v[156:159], v[148:151], v[2:5]
	ds_read_b128 v[132:135], v176 offset:0x1000
	s_waitcnt lgkmcnt(2)
	s_nop 0
	v_mfma_f32_16x16x32_bf16 v[126:129], v[172:175], v[160:163], v[126:129]
	v_mfma_f32_16x16x32_bf16 v[122:125], v[172:175], v[164:167], v[122:125]
	v_mfma_f32_16x16x32_bf16 v[118:121], v[172:175], v[168:171], v[118:121]
	v_mfma_f32_16x16x32_bf16 v[114:117], v[172:175], v[152:155], v[114:117]
	ds_read_b128 v[140:143], v176 offset:0x1800
	s_waitcnt lgkmcnt(2)
	s_nop 0
	v_mfma_f32_16x16x32_bf16 v[110:113], v[202:205], v[160:163], v[110:113]
	v_mfma_f32_16x16x32_bf16 v[106:109], v[202:205], v[164:167], v[106:109]
	v_mfma_f32_16x16x32_bf16 v[102:105], v[202:205], v[168:171], v[102:105]
	v_mfma_f32_16x16x32_bf16 v[98:101], v[202:205], v[152:155], v[98:101]
	ds_read_b128 v[144:147], v176 offset:0x2000
	s_waitcnt lgkmcnt(2)
	s_nop 0
	v_mfma_f32_16x16x32_bf16 v[94:97], v[132:135], v[160:163], v[94:97]
	v_mfma_f32_16x16x32_bf16 v[90:93], v[132:135], v[164:167], v[90:93]
	v_mfma_f32_16x16x32_bf16 v[86:89], v[132:135], v[168:171], v[86:89]
	v_mfma_f32_16x16x32_bf16 v[82:85], v[132:135], v[152:155], v[82:85]
	ds_read_b128 v[132:135], v176 offset:0x2800
	s_waitcnt lgkmcnt(2)
	s_nop 0
	v_mfma_f32_16x16x32_bf16 v[78:81], v[140:143], v[160:163], v[78:81]
	v_mfma_f32_16x16x32_bf16 v[74:77], v[140:143], v[164:167], v[74:77]
	v_mfma_f32_16x16x32_bf16 v[70:73], v[140:143], v[168:171], v[70:73]
	v_mfma_f32_16x16x32_bf16 v[66:69], v[140:143], v[152:155], v[66:69]
	ds_read_b128 v[140:143], v176 offset:0x3000
	s_waitcnt lgkmcnt(2)
	s_nop 0
	v_mfma_f32_16x16x32_bf16 v[62:65], v[144:147], v[160:163], v[62:65]
	v_mfma_f32_16x16x32_bf16 v[58:61], v[144:147], v[164:167], v[58:61]
	v_mfma_f32_16x16x32_bf16 v[54:57], v[144:147], v[168:171], v[54:57]
	v_mfma_f32_16x16x32_bf16 v[50:53], v[144:147], v[152:155], v[50:53]
	ds_read_b128 v[144:147], v176 offset:0x3800
	s_waitcnt lgkmcnt(2)
	s_nop 0
	v_mfma_f32_16x16x32_bf16 v[46:49], v[132:135], v[160:163], v[46:49]
	v_mfma_f32_16x16x32_bf16 v[42:45], v[132:135], v[164:167], v[42:45]
	v_mfma_f32_16x16x32_bf16 v[38:41], v[132:135], v[168:171], v[38:41]
	v_mfma_f32_16x16x32_bf16 v[34:37], v[132:135], v[152:155], v[34:37]
	s_waitcnt lgkmcnt(1)
	s_nop 0
	v_mfma_f32_16x16x32_bf16 v[30:33], v[140:143], v[160:163], v[30:33]
	v_mfma_f32_16x16x32_bf16 v[26:29], v[140:143], v[164:167], v[26:29]
	v_mfma_f32_16x16x32_bf16 v[22:25], v[140:143], v[168:171], v[22:25]
	v_mfma_f32_16x16x32_bf16 v[18:21], v[140:143], v[152:155], v[18:21]
	s_waitcnt lgkmcnt(0)
	s_nop 0
	v_mfma_f32_16x16x32_bf16 v[14:17], v[144:147], v[160:163], v[14:17]
	v_mfma_f32_16x16x32_bf16 v[10:13], v[144:147], v[164:167], v[10:13]
	v_mfma_f32_16x16x32_bf16 v[6:9], v[144:147], v[168:171], v[6:9]
	v_mfma_f32_16x16x32_bf16 v[2:5], v[144:147], v[152:155], v[2:5]
	s_setprio 0
	s_waitcnt vmcnt(0)
	s_add_i32 s13, s13, 0x10000
	s_addk_i32 s15, 0x80
	s_cmp_eq_u32 s15, 0x30480
	s_barrier
	s_cbranch_scc1 .LBB0_75
	s_branch .LBB0_73

.LBB0_271:
	s_cmp_eq_u32 s21, 0x60800
	s_mov_b32 s2, 0x10000
	s_cbranch_scc1 .LBB0_270
	s_and_b32 s2, s19, 0x10000
	s_xor_b32 s10, s2, 0x10000
	s_add_i32 s51, s29, s10
	s_add_i32 s52, s21, 0xfffa0000
	s_add_i32 s53, s51, 0x8000
	s_mov_b32 s10, s66
	s_mov_b32 s11, s67
	s_waitcnt lgkmcnt(0)
	v_add_u32_e32 v0, s2, v205
	v_add_u32_e32 v158, s2, v202
	v_xor_b32_e32 v177, 64, v0
	ds_read_b128 v[130:133], v158 offset:0
	ds_read_b128 v[134:137], v158 offset:0x800
	ds_read_b128 v[138:141], v158 offset:0x1000
	ds_read_b128 v[142:145], v158 offset:0x1800
	ds_read_b128 v[146:149], v0 offset:0
	ds_read_b128 v[150:153], v0 offset:0x800
	s_setprio 1
	ds_read_b128 v[154:157], v0 offset:0x1000
	s_mov_b32 m0, s51
	s_nop 0
	buffer_load_dwordx4 v173, s[64:67], s52 offen lds
	s_mov_b32 m0, s53
	s_nop 0
	buffer_load_dwordx4 v173, s[8:11], s52 offen lds
	s_waitcnt lgkmcnt(2)
	s_nop 0
	v_mfma_f32_16x16x32_bf16 v[122:125], v[146:149], v[130:133], v[122:125]
	v_mfma_f32_16x16x32_bf16 v[126:129], v[146:149], v[134:137], v[126:129]
	v_mfma_f32_16x16x32_bf16 v[118:121], v[146:149], v[138:141], v[118:121]
	v_mfma_f32_16x16x32_bf16 v[114:117], v[146:149], v[142:145], v[114:117]
	s_add_i32 m0, s51, 0x2000
	s_add_i32 s52, s21, 0xfffc0000
	buffer_load_dwordx4 v173, s[64:67], s52 offen lds
	ds_read_b128 v[146:149], v0 offset:0x1800
	s_waitcnt lgkmcnt(2)
	s_nop 0
	v_mfma_f32_16x16x32_bf16 v[110:113], v[150:153], v[130:133], v[110:113]
	v_mfma_f32_16x16x32_bf16 v[106:109], v[150:153], v[134:137], v[106:109]
	v_mfma_f32_16x16x32_bf16 v[102:105], v[150:153], v[138:141], v[102:105]
	v_mfma_f32_16x16x32_bf16 v[98:101], v[150:153], v[142:145], v[98:101]
	s_add_i32 m0, s51, 0xa000
	s_nop 0
	buffer_load_dwordx4 v173, s[8:11], s52 offen lds
	ds_read_b128 v[150:153], v0 offset:0x2000
	s_waitcnt lgkmcnt(2)
	s_nop 0
	v_mfma_f32_16x16x32_bf16 v[94:97], v[154:157], v[130:133], v[94:97]
	v_mfma_f32_16x16x32_bf16 v[90:93], v[154:157], v[134:137], v[90:93]
	v_mfma_f32_16x16x32_bf16 v[86:89], v[154:157], v[138:141], v[86:89]
	v_mfma_f32_16x16x32_bf16 v[82:85], v[154:157], v[142:145], v[82:85]
	s_add_i32 m0, s51, 0x4000
	s_add_i32 s52, s21, 0xfffe0000
	buffer_load_dwordx4 v173, s[64:67], s52 offen lds
	ds_read_b128 v[154:157], v0 offset:0x2800
	s_waitcnt lgkmcnt(2)
	s_nop 0
	v_mfma_f32_16x16x32_bf16 v[78:81], v[146:149], v[130:133], v[78:81]
	v_mfma_f32_16x16x32_bf16 v[74:77], v[146:149], v[134:137], v[74:77]
	v_mfma_f32_16x16x32_bf16 v[70:73], v[146:149], v[138:141], v[70:73]
	v_mfma_f32_16x16x32_bf16 v[66:69], v[146:149], v[142:145], v[66:69]
	s_add_i32 m0, s51, 0xc000
	s_nop 0
	buffer_load_dwordx4 v173, s[8:11], s52 offen lds
	ds_read_b128 v[146:149], v0 offset:0x3000
	s_waitcnt lgkmcnt(2)
	s_nop 0
	v_mfma_f32_16x16x32_bf16 v[62:65], v[150:153], v[130:133], v[62:65]
	v_mfma_f32_16x16x32_bf16 v[58:61], v[150:153], v[134:137], v[58:61]
	v_mfma_f32_16x16x32_bf16 v[54:57], v[150:153], v[138:141], v[54:57]
	v_mfma_f32_16x16x32_bf16 v[50:53], v[150:153], v[142:145], v[50:53]
	s_add_i32 m0, s51, 0x6000
	s_nop 0
	buffer_load_dwordx4 v173, s[64:67], s21 offen lds
	ds_read_b128 v[150:153], v0 offset:0x3800
	s_waitcnt lgkmcnt(2)
	v_xor_b32_e32 v0, 64, v158
	v_mfma_f32_16x16x32_bf16 v[46:49], v[154:157], v[130:133], v[46:49]
	v_mfma_f32_16x16x32_bf16 v[42:45], v[154:157], v[134:137], v[42:45]
	v_mfma_f32_16x16x32_bf16 v[38:41], v[154:157], v[138:141], v[38:41]
	v_mfma_f32_16x16x32_bf16 v[34:37], v[154:157], v[142:145], v[34:37]
	s_add_i32 m0, s51, 0xe000
	s_nop 0
	buffer_load_dwordx4 v173, s[8:11], s21 offen lds
	ds_read_b128 v[154:157], v0 offset:0
	ds_read_b128 v[158:161], v0 offset:0x800
	ds_read_b128 v[162:165], v0 offset:0x1000
	s_waitcnt lgkmcnt(4)
	s_nop 0
	v_mfma_f32_16x16x32_bf16 v[30:33], v[146:149], v[130:133], v[30:33]
	v_mfma_f32_16x16x32_bf16 v[26:29], v[146:149], v[134:137], v[26:29]
	v_mfma_f32_16x16x32_bf16 v[22:25], v[146:149], v[138:141], v[22:25]
	v_mfma_f32_16x16x32_bf16 v[18:21], v[146:149], v[142:145], v[18:21]
	ds_read_b128 v[146:149], v0 offset:0x1800
	ds_read_b128 v[166:169], v177 offset:0
	ds_read_b128 v[206:209], v177 offset:0x800
	s_waitcnt lgkmcnt(6)
	s_nop 0
	v_mfma_f32_16x16x32_bf16 v[14:17], v[150:153], v[130:133], v[14:17]
	v_mfma_f32_16x16x32_bf16 v[10:13], v[150:153], v[134:137], v[10:13]
	v_mfma_f32_16x16x32_bf16 v[6:9], v[150:153], v[138:141], v[6:9]
	v_mfma_f32_16x16x32_bf16 v[2:5], v[150:153], v[142:145], v[2:5]
	ds_read_b128 v[130:133], v177 offset:0x1000
	s_waitcnt lgkmcnt(2)
	s_nop 0
	v_mfma_f32_16x16x32_bf16 v[122:125], v[166:169], v[154:157], v[122:125]
	v_mfma_f32_16x16x32_bf16 v[126:129], v[166:169], v[158:161], v[126:129]
	v_mfma_f32_16x16x32_bf16 v[118:121], v[166:169], v[162:165], v[118:121]
	v_mfma_f32_16x16x32_bf16 v[114:117], v[166:169], v[146:149], v[114:117]
	ds_read_b128 v[134:137], v177 offset:0x1800
	s_waitcnt lgkmcnt(2)
	s_nop 0
	v_mfma_f32_16x16x32_bf16 v[110:113], v[206:209], v[154:157], v[110:113]
	v_mfma_f32_16x16x32_bf16 v[106:109], v[206:209], v[158:161], v[106:109]
	v_mfma_f32_16x16x32_bf16 v[102:105], v[206:209], v[162:165], v[102:105]
	v_mfma_f32_16x16x32_bf16 v[98:101], v[206:209], v[146:149], v[98:101]
	ds_read_b128 v[138:141], v177 offset:0x2000
	s_waitcnt lgkmcnt(2)
	s_nop 0
	v_mfma_f32_16x16x32_bf16 v[94:97], v[130:133], v[154:157], v[94:97]
	v_mfma_f32_16x16x32_bf16 v[90:93], v[130:133], v[158:161], v[90:93]
	v_mfma_f32_16x16x32_bf16 v[86:89], v[130:133], v[162:165], v[86:89]
	v_mfma_f32_16x16x32_bf16 v[82:85], v[130:133], v[146:149], v[82:85]
	ds_read_b128 v[130:133], v177 offset:0x2800
	s_waitcnt lgkmcnt(2)
	s_nop 0
	v_mfma_f32_16x16x32_bf16 v[78:81], v[134:137], v[154:157], v[78:81]
	v_mfma_f32_16x16x32_bf16 v[74:77], v[134:137], v[158:161], v[74:77]
	v_mfma_f32_16x16x32_bf16 v[70:73], v[134:137], v[162:165], v[70:73]
	v_mfma_f32_16x16x32_bf16 v[66:69], v[134:137], v[146:149], v[66:69]
	ds_read_b128 v[134:137], v177 offset:0x3000
	s_waitcnt lgkmcnt(2)
	s_nop 0
	v_mfma_f32_16x16x32_bf16 v[62:65], v[138:141], v[154:157], v[62:65]
	v_mfma_f32_16x16x32_bf16 v[58:61], v[138:141], v[158:161], v[58:61]
	v_mfma_f32_16x16x32_bf16 v[54:57], v[138:141], v[162:165], v[54:57]
	v_mfma_f32_16x16x32_bf16 v[50:53], v[138:141], v[146:149], v[50:53]
	ds_read_b128 v[138:141], v177 offset:0x3800
	s_waitcnt lgkmcnt(2)
	s_nop 0
	v_mfma_f32_16x16x32_bf16 v[46:49], v[130:133], v[154:157], v[46:49]
	v_mfma_f32_16x16x32_bf16 v[42:45], v[130:133], v[158:161], v[42:45]
	v_mfma_f32_16x16x32_bf16 v[38:41], v[130:133], v[162:165], v[38:41]
	v_mfma_f32_16x16x32_bf16 v[34:37], v[130:133], v[146:149], v[34:37]
	s_waitcnt lgkmcnt(1)
	s_nop 0
	v_mfma_f32_16x16x32_bf16 v[30:33], v[134:137], v[154:157], v[30:33]
	v_mfma_f32_16x16x32_bf16 v[26:29], v[134:137], v[158:161], v[26:29]
	v_mfma_f32_16x16x32_bf16 v[22:25], v[134:137], v[162:165], v[22:25]
	v_mfma_f32_16x16x32_bf16 v[18:21], v[134:137], v[146:149], v[18:21]
	s_waitcnt lgkmcnt(0)
	s_nop 0
	v_mfma_f32_16x16x32_bf16 v[14:17], v[138:141], v[154:157], v[14:17]
	v_mfma_f32_16x16x32_bf16 v[10:13], v[138:141], v[158:161], v[10:13]
	v_mfma_f32_16x16x32_bf16 v[6:9], v[138:141], v[162:165], v[6:9]
	v_mfma_f32_16x16x32_bf16 v[2:5], v[138:141], v[146:149], v[2:5]
	s_setprio 0
	s_waitcnt vmcnt(0)
	s_add_i32 s19, s19, 0x10000
	s_addk_i32 s21, 0x80
	s_cmp_eq_u32 s21, 0x60880
	s_barrier
	s_cbranch_scc1 .LBB0_273
	s_branch .LBB0_271

.LBB0_296:
	s_and_b32 s2, s44, 0x10000
	s_cmp_ge_u32 s41, s24
	s_cbranch_scc1 .LBB0_295
	s_xor_b32 s14, s2, 0x10000
	s_add_i32 s46, s26, s14
	s_add_i32 s47, s46, 0x8000
	s_mov_b32 s14, s66
	s_mov_b32 s15, s67
	s_waitcnt lgkmcnt(0)
	v_add_u32_e32 v0, s2, v143
	v_add_u32_e32 v164, s2, v133
	v_xor_b32_e32 v176, 64, v0
	ds_read_b128 v[134:137], v164 offset:0
	ds_read_b128 v[138:141], v164 offset:0x800
	ds_read_b128 v[144:147], v164 offset:0x1000
	ds_read_b128 v[148:151], v164 offset:0x1800
	ds_read_b128 v[152:155], v0 offset:0
	ds_read_b128 v[156:159], v0 offset:0x800
	s_setprio 1
	ds_read_b128 v[160:163], v0 offset:0x1000
	s_mov_b32 m0, s46
	s_nop 0
	buffer_load_dwordx4 v131, s[64:67], s45 offen lds
	s_mov_b32 m0, s47
	s_add_i32 s47, s27, s45
	buffer_load_dwordx4 v131, s[12:15], s45 offen lds
	s_waitcnt lgkmcnt(2)
	s_nop 0
	v_mfma_f32_16x16x32_bf16 v[126:129], v[152:155], v[134:137], v[126:129]
	v_mfma_f32_16x16x32_bf16 v[122:125], v[152:155], v[138:141], v[122:125]
	v_mfma_f32_16x16x32_bf16 v[118:121], v[152:155], v[144:147], v[118:121]
	v_mfma_f32_16x16x32_bf16 v[114:117], v[152:155], v[148:151], v[114:117]
	s_add_i32 m0, s46, 0x2000
	s_nop 0
	buffer_load_dwordx4 v131, s[64:67], s47 offen lds
	ds_read_b128 v[152:155], v0 offset:0x1800
	s_waitcnt lgkmcnt(2)
	s_nop 0
	v_mfma_f32_16x16x32_bf16 v[110:113], v[156:159], v[134:137], v[110:113]
	v_mfma_f32_16x16x32_bf16 v[106:109], v[156:159], v[138:141], v[106:109]
	v_mfma_f32_16x16x32_bf16 v[102:105], v[156:159], v[144:147], v[102:105]
	v_mfma_f32_16x16x32_bf16 v[98:101], v[156:159], v[148:151], v[98:101]
	s_add_i32 m0, s46, 0xa000
	s_nop 0
	buffer_load_dwordx4 v131, s[12:15], s47 offen lds
	ds_read_b128 v[156:159], v0 offset:0x2000
	s_waitcnt lgkmcnt(2)
	s_nop 0
	v_mfma_f32_16x16x32_bf16 v[94:97], v[160:163], v[134:137], v[94:97]
	v_mfma_f32_16x16x32_bf16 v[90:93], v[160:163], v[138:141], v[90:93]
	v_mfma_f32_16x16x32_bf16 v[86:89], v[160:163], v[144:147], v[86:89]
	v_mfma_f32_16x16x32_bf16 v[82:85], v[160:163], v[148:151], v[82:85]
	s_add_i32 m0, s46, 0x4000
	s_add_i32 s47, s34, s45
	buffer_load_dwordx4 v131, s[64:67], s47 offen lds
	ds_read_b128 v[160:163], v0 offset:0x2800
	s_waitcnt lgkmcnt(2)
	s_nop 0
	v_mfma_f32_16x16x32_bf16 v[78:81], v[152:155], v[134:137], v[78:81]
	v_mfma_f32_16x16x32_bf16 v[74:77], v[152:155], v[138:141], v[74:77]
	v_mfma_f32_16x16x32_bf16 v[70:73], v[152:155], v[144:147], v[70:73]
	v_mfma_f32_16x16x32_bf16 v[66:69], v[152:155], v[148:151], v[66:69]
	s_add_i32 m0, s46, 0xc000
	s_nop 0
	buffer_load_dwordx4 v131, s[12:15], s47 offen lds
	ds_read_b128 v[152:155], v0 offset:0x3000
	s_waitcnt lgkmcnt(2)
	s_nop 0
	v_mfma_f32_16x16x32_bf16 v[62:65], v[156:159], v[134:137], v[62:65]
	v_mfma_f32_16x16x32_bf16 v[58:61], v[156:159], v[138:141], v[58:61]
	v_mfma_f32_16x16x32_bf16 v[54:57], v[156:159], v[144:147], v[54:57]
	v_mfma_f32_16x16x32_bf16 v[50:53], v[156:159], v[148:151], v[50:53]
	s_add_i32 m0, s46, 0x6000
	s_add_i32 s47, s37, s45
	buffer_load_dwordx4 v131, s[64:67], s47 offen lds
	ds_read_b128 v[156:159], v0 offset:0x3800
	s_waitcnt lgkmcnt(2)
	v_xor_b32_e32 v0, 64, v164
	v_mfma_f32_16x16x32_bf16 v[46:49], v[160:163], v[134:137], v[46:49]
	v_mfma_f32_16x16x32_bf16 v[42:45], v[160:163], v[138:141], v[42:45]
	v_mfma_f32_16x16x32_bf16 v[38:41], v[160:163], v[144:147], v[38:41]
	v_mfma_f32_16x16x32_bf16 v[34:37], v[160:163], v[148:151], v[34:37]
	s_add_i32 m0, s46, 0xe000
	s_nop 0
	buffer_load_dwordx4 v131, s[12:15], s47 offen lds
	ds_read_b128 v[160:163], v0 offset:0
	ds_read_b128 v[164:167], v0 offset:0x800
	ds_read_b128 v[168:171], v0 offset:0x1000
	s_waitcnt lgkmcnt(4)
	s_nop 0
	v_mfma_f32_16x16x32_bf16 v[30:33], v[152:155], v[134:137], v[30:33]
	v_mfma_f32_16x16x32_bf16 v[26:29], v[152:155], v[138:141], v[26:29]
	v_mfma_f32_16x16x32_bf16 v[22:25], v[152:155], v[144:147], v[22:25]
	v_mfma_f32_16x16x32_bf16 v[18:21], v[152:155], v[148:151], v[18:21]
	ds_read_b128 v[152:155], v0 offset:0x1800
	ds_read_b128 v[172:175], v176 offset:0
	ds_read_b128 v[202:205], v176 offset:0x800
	s_waitcnt lgkmcnt(6)
	s_nop 0
	v_mfma_f32_16x16x32_bf16 v[14:17], v[156:159], v[134:137], v[14:17]
	v_mfma_f32_16x16x32_bf16 v[10:13], v[156:159], v[138:141], v[10:13]
	v_mfma_f32_16x16x32_bf16 v[6:9], v[156:159], v[144:147], v[6:9]
	v_mfma_f32_16x16x32_bf16 v[2:5], v[156:159], v[148:151], v[2:5]
	ds_read_b128 v[134:137], v176 offset:0x1000
	s_waitcnt lgkmcnt(2)
	s_nop 0
	v_mfma_f32_16x16x32_bf16 v[126:129], v[172:175], v[160:163], v[126:129]
	v_mfma_f32_16x16x32_bf16 v[122:125], v[172:175], v[164:167], v[122:125]
	v_mfma_f32_16x16x32_bf16 v[118:121], v[172:175], v[168:171], v[118:121]
	v_mfma_f32_16x16x32_bf16 v[114:117], v[172:175], v[152:155], v[114:117]
	ds_read_b128 v[138:141], v176 offset:0x1800
	s_waitcnt lgkmcnt(2)
	s_nop 0
	v_mfma_f32_16x16x32_bf16 v[110:113], v[202:205], v[160:163], v[110:113]
	v_mfma_f32_16x16x32_bf16 v[106:109], v[202:205], v[164:167], v[106:109]
	v_mfma_f32_16x16x32_bf16 v[102:105], v[202:205], v[168:171], v[102:105]
	v_mfma_f32_16x16x32_bf16 v[98:101], v[202:205], v[152:155], v[98:101]
	ds_read_b128 v[144:147], v176 offset:0x2000
	s_waitcnt lgkmcnt(2)
	s_nop 0
	v_mfma_f32_16x16x32_bf16 v[94:97], v[134:137], v[160:163], v[94:97]
	v_mfma_f32_16x16x32_bf16 v[90:93], v[134:137], v[164:167], v[90:93]
	v_mfma_f32_16x16x32_bf16 v[86:89], v[134:137], v[168:171], v[86:89]
	v_mfma_f32_16x16x32_bf16 v[82:85], v[134:137], v[152:155], v[82:85]
	ds_read_b128 v[134:137], v176 offset:0x2800
	s_waitcnt lgkmcnt(2)
	s_nop 0
	v_mfma_f32_16x16x32_bf16 v[78:81], v[138:141], v[160:163], v[78:81]
	v_mfma_f32_16x16x32_bf16 v[74:77], v[138:141], v[164:167], v[74:77]
	v_mfma_f32_16x16x32_bf16 v[70:73], v[138:141], v[168:171], v[70:73]
	v_mfma_f32_16x16x32_bf16 v[66:69], v[138:141], v[152:155], v[66:69]
	ds_read_b128 v[138:141], v176 offset:0x3000
	s_waitcnt lgkmcnt(2)
	s_nop 0
	v_mfma_f32_16x16x32_bf16 v[62:65], v[144:147], v[160:163], v[62:65]
	v_mfma_f32_16x16x32_bf16 v[58:61], v[144:147], v[164:167], v[58:61]
	v_mfma_f32_16x16x32_bf16 v[54:57], v[144:147], v[168:171], v[54:57]
	v_mfma_f32_16x16x32_bf16 v[50:53], v[144:147], v[152:155], v[50:53]
	ds_read_b128 v[144:147], v176 offset:0x3800
	s_waitcnt lgkmcnt(2)
	s_nop 0
	v_mfma_f32_16x16x32_bf16 v[46:49], v[134:137], v[160:163], v[46:49]
	v_mfma_f32_16x16x32_bf16 v[42:45], v[134:137], v[164:167], v[42:45]
	v_mfma_f32_16x16x32_bf16 v[38:41], v[134:137], v[168:171], v[38:41]
	v_mfma_f32_16x16x32_bf16 v[34:37], v[134:137], v[152:155], v[34:37]
	s_waitcnt lgkmcnt(1)
	s_nop 0
	v_mfma_f32_16x16x32_bf16 v[30:33], v[138:141], v[160:163], v[30:33]
	v_mfma_f32_16x16x32_bf16 v[26:29], v[138:141], v[164:167], v[26:29]
	v_mfma_f32_16x16x32_bf16 v[22:25], v[138:141], v[168:171], v[22:25]
	v_mfma_f32_16x16x32_bf16 v[18:21], v[138:141], v[152:155], v[18:21]
	s_waitcnt lgkmcnt(0)
	s_nop 0
	v_mfma_f32_16x16x32_bf16 v[14:17], v[144:147], v[160:163], v[14:17]
	v_mfma_f32_16x16x32_bf16 v[10:13], v[144:147], v[164:167], v[10:13]
	v_mfma_f32_16x16x32_bf16 v[6:9], v[144:147], v[168:171], v[6:9]
	v_mfma_f32_16x16x32_bf16 v[2:5], v[144:147], v[152:155], v[2:5]
	s_setprio 0
	s_waitcnt vmcnt(0)
	s_add_i32 s44, s44, 0x10000
	s_addk_i32 s45, 0x80
	s_add_i32 s41, s41, 1
	s_cmp_eq_u32 s39, s44
	s_barrier
	s_cbranch_scc1 .LBB0_298
	s_branch .LBB0_296
